# v24 + S5 pass B task prologue: all earlier-segment end states fetched first, Horner chain from registers (one memory round trip instead of up to seven)
# speedup vs baseline: 1.0047x; 1.0047x over previous
; template <bool FULL>
; __device__ __forceinline__ void s5_pass(const Params& P, LAS unsigned char* lds, int bx, int tid_in) {
;     ...
;         if (FULL && seg > 0) {
;             float p0r = ar0, p0i = ai0, p1r = ar1, p1i = ai1;
; #pragma unroll
;             for (int q = 0; q < 9; ++q) { const float a = p0r * p0r - p0i * p0i, b2 = 2.f * p0r * p0i, c = p1r * p1r - p1i * p1i, d2 = 2.f * p1r * p1i; p0r = a; p0i = b2; p1r = c; p1i = d2; }
;             for (int j = 0; j < seg; ++j) { const f32x4 e = SEG[(size_t)(task - (seg - j) * 512) * 64 + lane];
;                 const float n0r = p0r * h0r - p0i * h0i + e[0], n0i = p0r * h0i + p0i * h0r + e[1], n1r = p1r * h1r - p1i * h1i + e[2], n1i = p1r * h1i + p1i * h1r + e[3];
;                 h0r = n0r; h0i = n0i; h1r = n1r; h1i = n1i; }
;         }
.LBB0_421:
	s_ashr_i32 s51, s50, 31
	s_lshl_b64 s[64:65], s[50:51], 10
	v_lshl_add_u64 v[10:11], v[138:139], 0, s[64:65]
	s_mov_b32 s64, 0x80000
	s_mov_b32 s65, 0
	global_load_dwordx4 v[34:37], v[10:11], off
	s_cmp_eq_u32 s40, 1
	s_cbranch_scc1 .Lseg_issued
	v_lshl_add_u64 v[10:11], v[10:11], 0, s[64:65]
	global_load_dwordx4 v[38:41], v[10:11], off
	s_cmp_eq_u32 s40, 2
	s_cbranch_scc1 .Lseg_issued
	v_lshl_add_u64 v[10:11], v[10:11], 0, s[64:65]
	global_load_dwordx4 v[42:45], v[10:11], off
	s_cmp_eq_u32 s40, 3
	s_cbranch_scc1 .Lseg_issued
	v_lshl_add_u64 v[10:11], v[10:11], 0, s[64:65]
	global_load_dwordx4 v[46:49], v[10:11], off
	s_cmp_eq_u32 s40, 4
	s_cbranch_scc1 .Lseg_issued
	v_lshl_add_u64 v[10:11], v[10:11], 0, s[64:65]
	global_load_dwordx4 v[236:239], v[10:11], off
	s_cmp_eq_u32 s40, 5
	s_cbranch_scc1 .Lseg_issued
	v_lshl_add_u64 v[10:11], v[10:11], 0, s[64:65]
	global_load_dwordx4 v[240:243], v[10:11], off
	s_cmp_eq_u32 s40, 6
	s_cbranch_scc1 .Lseg_issued
	v_lshl_add_u64 v[10:11], v[10:11], 0, s[64:65]
	global_load_dwordx4 v[244:247], v[10:11], off
.Lseg_issued:
	s_waitcnt vmcnt(0)
	v_pk_mul_f32 v[14:15], v[2:3], v[32:33] op_sel:[0,1] op_sel_hi:[1,0]
	v_pk_mul_f32 v[16:17], v[6:7], v[52:53] op_sel:[0,1] op_sel_hi:[1,0]
	v_pk_fma_f32 v[18:19], v[0:1], v[32:33], v[14:15] neg_lo:[0,0,1] neg_hi:[0,0,1]
	v_pk_fma_f32 v[14:15], v[0:1], v[32:33], v[14:15]
	v_pk_fma_f32 v[20:21], v[4:5], v[52:53], v[16:17] neg_lo:[0,0,1] neg_hi:[0,0,1]
	v_pk_fma_f32 v[16:17], v[4:5], v[52:53], v[16:17]
	v_mov_b32_e32 v19, v15
	v_mov_b32_e32 v21, v17
	v_pk_add_f32 v[32:33], v[18:19], v[34:35]
	v_pk_add_f32 v[52:53], v[20:21], v[36:37]
	s_cmp_eq_u32 s40, 1
	s_cbranch_scc1 .Lseg_done
	v_pk_mul_f32 v[14:15], v[2:3], v[32:33] op_sel:[0,1] op_sel_hi:[1,0]
	v_pk_mul_f32 v[16:17], v[6:7], v[52:53] op_sel:[0,1] op_sel_hi:[1,0]
	v_pk_fma_f32 v[18:19], v[0:1], v[32:33], v[14:15] neg_lo:[0,0,1] neg_hi:[0,0,1]
	v_pk_fma_f32 v[14:15], v[0:1], v[32:33], v[14:15]
	v_pk_fma_f32 v[20:21], v[4:5], v[52:53], v[16:17] neg_lo:[0,0,1] neg_hi:[0,0,1]
	v_pk_fma_f32 v[16:17], v[4:5], v[52:53], v[16:17]
	v_mov_b32_e32 v19, v15
	v_mov_b32_e32 v21, v17
	v_pk_add_f32 v[32:33], v[18:19], v[38:39]
	v_pk_add_f32 v[52:53], v[20:21], v[40:41]
	s_cmp_eq_u32 s40, 2
	s_cbranch_scc1 .Lseg_done
	v_pk_mul_f32 v[14:15], v[2:3], v[32:33] op_sel:[0,1] op_sel_hi:[1,0]
	v_pk_mul_f32 v[16:17], v[6:7], v[52:53] op_sel:[0,1] op_sel_hi:[1,0]
	v_pk_fma_f32 v[18:19], v[0:1], v[32:33], v[14:15] neg_lo:[0,0,1] neg_hi:[0,0,1]
	v_pk_fma_f32 v[14:15], v[0:1], v[32:33], v[14:15]
	v_pk_fma_f32 v[20:21], v[4:5], v[52:53], v[16:17] neg_lo:[0,0,1] neg_hi:[0,0,1]
	v_pk_fma_f32 v[16:17], v[4:5], v[52:53], v[16:17]
	v_mov_b32_e32 v19, v15
	v_mov_b32_e32 v21, v17
	v_pk_add_f32 v[32:33], v[18:19], v[42:43]
	v_pk_add_f32 v[52:53], v[20:21], v[44:45]
	s_cmp_eq_u32 s40, 3
	s_cbranch_scc1 .Lseg_done
	v_pk_mul_f32 v[14:15], v[2:3], v[32:33] op_sel:[0,1] op_sel_hi:[1,0]
	v_pk_mul_f32 v[16:17], v[6:7], v[52:53] op_sel:[0,1] op_sel_hi:[1,0]
	v_pk_fma_f32 v[18:19], v[0:1], v[32:33], v[14:15] neg_lo:[0,0,1] neg_hi:[0,0,1]
	v_pk_fma_f32 v[14:15], v[0:1], v[32:33], v[14:15]
	v_pk_fma_f32 v[20:21], v[4:5], v[52:53], v[16:17] neg_lo:[0,0,1] neg_hi:[0,0,1]
	v_pk_fma_f32 v[16:17], v[4:5], v[52:53], v[16:17]
	v_mov_b32_e32 v19, v15
	v_mov_b32_e32 v21, v17
	v_pk_add_f32 v[32:33], v[18:19], v[46:47]
	v_pk_add_f32 v[52:53], v[20:21], v[48:49]
	s_cmp_eq_u32 s40, 4
	s_cbranch_scc1 .Lseg_done
	v_pk_mul_f32 v[14:15], v[2:3], v[32:33] op_sel:[0,1] op_sel_hi:[1,0]
	v_pk_mul_f32 v[16:17], v[6:7], v[52:53] op_sel:[0,1] op_sel_hi:[1,0]
	v_pk_fma_f32 v[18:19], v[0:1], v[32:33], v[14:15] neg_lo:[0,0,1] neg_hi:[0,0,1]
	v_pk_fma_f32 v[14:15], v[0:1], v[32:33], v[14:15]
	v_pk_fma_f32 v[20:21], v[4:5], v[52:53], v[16:17] neg_lo:[0,0,1] neg_hi:[0,0,1]
	v_pk_fma_f32 v[16:17], v[4:5], v[52:53], v[16:17]
	v_mov_b32_e32 v19, v15
	v_mov_b32_e32 v21, v17
	v_pk_add_f32 v[32:33], v[18:19], v[236:237]
	v_pk_add_f32 v[52:53], v[20:21], v[238:239]
	s_cmp_eq_u32 s40, 5
	s_cbranch_scc1 .Lseg_done
	v_pk_mul_f32 v[14:15], v[2:3], v[32:33] op_sel:[0,1] op_sel_hi:[1,0]
	v_pk_mul_f32 v[16:17], v[6:7], v[52:53] op_sel:[0,1] op_sel_hi:[1,0]
	v_pk_fma_f32 v[18:19], v[0:1], v[32:33], v[14:15] neg_lo:[0,0,1] neg_hi:[0,0,1]
	v_pk_fma_f32 v[14:15], v[0:1], v[32:33], v[14:15]
	v_pk_fma_f32 v[20:21], v[4:5], v[52:53], v[16:17] neg_lo:[0,0,1] neg_hi:[0,0,1]
	v_pk_fma_f32 v[16:17], v[4:5], v[52:53], v[16:17]
	v_mov_b32_e32 v19, v15
	v_mov_b32_e32 v21, v17
	v_pk_add_f32 v[32:33], v[18:19], v[240:241]
	v_pk_add_f32 v[52:53], v[20:21], v[242:243]
	s_cmp_eq_u32 s40, 6
	s_cbranch_scc1 .Lseg_done
	v_pk_mul_f32 v[14:15], v[2:3], v[32:33] op_sel:[0,1] op_sel_hi:[1,0]
	v_pk_mul_f32 v[16:17], v[6:7], v[52:53] op_sel:[0,1] op_sel_hi:[1,0]
	v_pk_fma_f32 v[18:19], v[0:1], v[32:33], v[14:15] neg_lo:[0,0,1] neg_hi:[0,0,1]
	v_pk_fma_f32 v[14:15], v[0:1], v[32:33], v[14:15]
	v_pk_fma_f32 v[20:21], v[4:5], v[52:53], v[16:17] neg_lo:[0,0,1] neg_hi:[0,0,1]
	v_pk_fma_f32 v[16:17], v[4:5], v[52:53], v[16:17]
	v_mov_b32_e32 v19, v15
	v_mov_b32_e32 v21, v17
	v_pk_add_f32 v[32:33], v[18:19], v[244:245]
	v_pk_add_f32 v[52:53], v[20:21], v[246:247]
.Lseg_done:
	s_branch .LBB0_423
.LBB0_422:
	v_mov_b32_e32 v126, v127
	v_mov_b64_e32 v[52:53], v[126:127]
	v_mov_b64_e32 v[32:33], v[126:127]
